# P0: counted waits recomputed so the A/B double buffers of the weight-conversion loop and the x-row loop really overlap the next item's loads
# speedup vs baseline: 1.0040x; 1.0003x over previous
.LBB0_30:
	s_ashr_i32 s40, s38, 5
	s_abs_i32 s41, s40
	v_cvt_f32_u32_e32 v100, s41
	s_waitcnt vmcnt(63)
	ds_write2_b32 v60, v61, v62 offset1:66
	s_waitcnt vmcnt(63)
	ds_write2_b32 v60, v63, v64 offset0:132 offset1:198
	s_waitcnt vmcnt(62)
	ds_write2_b32 v99, v65, v66 offset0:8 offset1:74
	s_waitcnt vmcnt(60)
	ds_write2_b32 v99, v67, v68 offset0:140 offset1:206
	s_waitcnt vmcnt(58)
	ds_write2_b32 v93, v69, v70 offset0:16 offset1:82
	s_waitcnt vmcnt(56)
	ds_write2_b32 v93, v71, v72 offset0:148 offset1:214
	s_waitcnt vmcnt(54)
	ds_write2_b32 v94, v73, v74 offset0:24 offset1:90
	s_waitcnt vmcnt(52)
	ds_write2_b32 v94, v75, v76 offset0:156 offset1:222
	s_waitcnt vmcnt(50)
	ds_write2_b32 v95, v77, v78 offset0:32 offset1:98
	s_waitcnt vmcnt(48)
	ds_write2_b32 v95, v79, v80 offset0:164 offset1:230
	s_waitcnt vmcnt(46)
	ds_write2_b32 v96, v81, v82 offset0:40 offset1:106
	s_waitcnt vmcnt(44)
	ds_write2_b32 v96, v83, v84 offset0:172 offset1:238
	s_waitcnt vmcnt(42)
	ds_write2_b32 v97, v85, v86 offset0:48 offset1:114
	s_waitcnt vmcnt(40)
	ds_write2_b32 v97, v87, v88 offset0:180 offset1:246
	s_waitcnt vmcnt(38)
	ds_write2_b32 v98, v89, v90 offset0:56 offset1:122
	s_waitcnt vmcnt(36)
	ds_write2_b32 v98, v91, v92 offset0:188 offset1:254
	v_rcp_iflag_f32_e32 v100, v100
	s_waitcnt lgkmcnt(0)
	ds_read2_b32 v[94:95], v56 offset1:33
	s_sub_i32 s49, 0, s41
	v_mul_f32_e32 v99, 0x4f7ffffe, v100
	v_cvt_u32_f32_e32 v99, v99
	s_abs_i32 s42, s48
	s_waitcnt lgkmcnt(0)
	v_mul_f32_e32 v93, v44, v94
	v_mul_f32_e32 v94, v45, v95
	v_readfirstlane_b32 s50, v99
	v_cvt_pk_bf16_f32 v94, v93, v94
	ds_read2_b32 v[96:97], v56 offset0:66 offset1:99
	s_mul_i32 s49, s49, s50
	s_mul_hi_u32 s49, s50, s49
	s_add_i32 s50, s50, s49
	s_mul_hi_u32 s49, s42, s50
	s_mul_i32 s50, s49, s41
	s_waitcnt lgkmcnt(0)
	v_mul_f32_e32 v95, v47, v97
	s_xor_b32 s43, s48, s40
	s_sub_i32 s42, s42, s50
	v_mul_f32_e32 v93, v46, v96
	v_cvt_pk_bf16_f32 v95, v93, v95
	ds_read2_b32 v[96:97], v56 offset0:132 offset1:165
	s_ashr_i32 s43, s43, 31
	s_add_i32 s50, s49, 1
	s_sub_i32 s51, s42, s41
	s_cmp_ge_u32 s42, s41
	s_cselect_b32 s49, s50, s49
	s_cselect_b32 s42, s51, s42
	s_add_i32 s50, s49, 1
	s_cmp_ge_u32 s42, s41
	s_waitcnt lgkmcnt(0)
	v_mul_f32_e32 v93, v40, v96
	v_mul_f32_e32 v96, v41, v97
	s_cselect_b32 s41, s50, s49
	v_cvt_pk_bf16_f32 v96, v93, v96
	ds_read2_b32 v[98:99], v56 offset0:198 offset1:231
	s_xor_b32 s41, s41, s43
	s_sub_i32 s41, s41, s43
	s_mul_i32 s42, s41, s40
	s_lshl_b32 s40, s41, 6
	s_sub_i32 s41, s48, s42
	s_lshl_b32 s49, s41, 5
	s_waitcnt lgkmcnt(0)
	v_mul_f32_e32 v93, v42, v98
	v_mul_f32_e32 v97, v43, v99
	v_cvt_pk_bf16_f32 v97, v93, v97
	v_or_b32_e32 v93, s49, v55
	ds_read2_b32 v[100:101], v56 offset0:8 offset1:41
	s_ashr_i32 s41, s40, 31
	v_mad_i64_i32 v[98:99], s[42:43], v93, s47, 0
	v_lshl_add_u64 v[98:99], v[98:99], 1, s[36:37]
	s_lshl_b64 s[40:41], s[40:41], 1
	v_lshl_add_u64 v[98:99], v[98:99], 0, s[40:41]
	v_lshl_add_u64 v[98:99], v[98:99], 0, v[52:53]
	global_store_dwordx4 v[98:99], v[94:97], off
	s_waitcnt lgkmcnt(0)
	v_mul_f32_e32 v93, v44, v100
	v_mul_f32_e32 v94, v45, v101
	v_cvt_pk_bf16_f32 v94, v93, v94
	ds_read2_b32 v[96:97], v56 offset0:74 offset1:107
	s_waitcnt lgkmcnt(0)
	v_mul_f32_e32 v95, v47, v97
	v_mul_f32_e32 v93, v46, v96
	v_cvt_pk_bf16_f32 v95, v93, v95
	ds_read2_b32 v[96:97], v56 offset0:140 offset1:173
	s_waitcnt lgkmcnt(0)
	v_mul_f32_e32 v93, v40, v96
	v_mul_f32_e32 v96, v41, v97
	v_cvt_pk_bf16_f32 v96, v93, v96
	ds_read2_b32 v[98:99], v56 offset0:206 offset1:239
	s_waitcnt lgkmcnt(0)
	v_mul_f32_e32 v93, v42, v98
	v_mul_f32_e32 v97, v43, v99
	v_cvt_pk_bf16_f32 v97, v93, v97
	v_or_b32_e32 v93, s49, v57
	ds_read2_b32 v[100:101], v56 offset0:16 offset1:49
	v_mad_i64_i32 v[98:99], s[42:43], v93, s47, 0
	v_lshl_add_u64 v[98:99], v[98:99], 1, s[36:37]
	v_lshl_add_u64 v[98:99], v[98:99], 0, s[40:41]
	v_lshl_add_u64 v[98:99], v[98:99], 0, v[52:53]
	global_store_dwordx4 v[98:99], v[94:97], off
	s_waitcnt lgkmcnt(0)
	v_mul_f32_e32 v93, v44, v100
	v_mul_f32_e32 v94, v45, v101
	v_cvt_pk_bf16_f32 v94, v93, v94
	ds_read2_b32 v[96:97], v56 offset0:82 offset1:115
	s_waitcnt lgkmcnt(0)
	v_mul_f32_e32 v95, v47, v97
	v_mul_f32_e32 v93, v46, v96
	v_cvt_pk_bf16_f32 v95, v93, v95
	ds_read2_b32 v[96:97], v56 offset0:148 offset1:181
	s_waitcnt lgkmcnt(0)
	v_mul_f32_e32 v93, v40, v96
	v_mul_f32_e32 v96, v41, v97
	v_cvt_pk_bf16_f32 v96, v93, v96
	ds_read2_b32 v[98:99], v56 offset0:214 offset1:247
	s_waitcnt lgkmcnt(0)
	v_mul_f32_e32 v93, v42, v98
	v_mul_f32_e32 v97, v43, v99
	v_cvt_pk_bf16_f32 v97, v93, v97
	v_or_b32_e32 v93, s49, v58
	ds_read2_b32 v[100:101], v56 offset0:24 offset1:57
	v_mad_i64_i32 v[98:99], s[42:43], v93, s47, 0
	v_lshl_add_u64 v[98:99], v[98:99], 1, s[36:37]
	v_lshl_add_u64 v[98:99], v[98:99], 0, s[40:41]
	v_lshl_add_u64 v[98:99], v[98:99], 0, v[52:53]
	global_store_dwordx4 v[98:99], v[94:97], off
	s_waitcnt lgkmcnt(0)
	v_mul_f32_e32 v93, v44, v100
	v_mul_f32_e32 v94, v45, v101
	v_cvt_pk_bf16_f32 v94, v93, v94
	ds_read2_b32 v[96:97], v56 offset0:90 offset1:123
	s_waitcnt lgkmcnt(0)
	v_mul_f32_e32 v95, v47, v97
	v_mul_f32_e32 v93, v46, v96
	v_cvt_pk_bf16_f32 v95, v93, v95
	ds_read2_b32 v[96:97], v56 offset0:156 offset1:189
	s_waitcnt lgkmcnt(0)
	v_mul_f32_e32 v93, v40, v96
	v_mul_f32_e32 v96, v41, v97
	v_cvt_pk_bf16_f32 v96, v93, v96
	ds_read2_b32 v[98:99], v56 offset0:222 offset1:255
	s_waitcnt lgkmcnt(0)
	v_mul_f32_e32 v93, v42, v98
	v_mul_f32_e32 v97, v43, v99
	v_cvt_pk_bf16_f32 v97, v93, v97
	v_or_b32_e32 v93, s49, v59
	v_mad_i64_i32 v[98:99], s[42:43], v93, s47, 0
	v_lshl_add_u64 v[98:99], v[98:99], 1, s[36:37]
	v_lshl_add_u64 v[98:99], v[98:99], 0, s[40:41]
	v_lshl_add_u64 v[52:53], v[98:99], 0, v[52:53]
	global_store_dwordx4 v[52:53], v[94:97], off
	s_waitcnt lgkmcnt(0)

.LBB0_41:
	v_add_u32_e32 v99, 0x400, v60
	v_add_u32_e32 v93, 0x800, v60
	v_add_u32_e32 v94, 0xc00, v60
	v_add_u32_e32 v95, 0x1000, v60
	v_add_u32_e32 v96, 0x1400, v60
	v_add_u32_e32 v97, 0x1800, v60
	v_add_u32_e32 v98, 0x1c00, v60
	s_waitcnt vmcnt(62)
	ds_write2_b32 v60, v0, v1 offset1:66
	s_waitcnt vmcnt(60)
	ds_write2_b32 v60, v2, v3 offset0:132 offset1:198
	s_waitcnt vmcnt(58)
	ds_write2_b32 v99, v4, v5 offset0:8 offset1:74
	s_waitcnt vmcnt(56)
	ds_write2_b32 v99, v6, v7 offset0:140 offset1:206
	s_waitcnt vmcnt(54)
	ds_write2_b32 v93, v8, v9 offset0:16 offset1:82
	s_waitcnt vmcnt(52)
	ds_write2_b32 v93, v10, v11 offset0:148 offset1:214
	s_waitcnt vmcnt(50)
	ds_write2_b32 v94, v12, v13 offset0:24 offset1:90
	s_waitcnt vmcnt(48)
	ds_write2_b32 v94, v14, v15 offset0:156 offset1:222
	s_waitcnt vmcnt(46)
	ds_write2_b32 v95, v16, v17 offset0:32 offset1:98
	s_waitcnt vmcnt(44)
	ds_write2_b32 v95, v18, v19 offset0:164 offset1:230
	s_waitcnt vmcnt(42)
	ds_write2_b32 v96, v20, v21 offset0:40 offset1:106
	s_waitcnt vmcnt(40)
	ds_write2_b32 v96, v22, v23 offset0:172 offset1:238
	s_waitcnt vmcnt(38)
	ds_write2_b32 v97, v24, v25 offset0:48 offset1:114
	s_waitcnt vmcnt(36)
	ds_write2_b32 v97, v26, v27 offset0:180 offset1:246
	s_waitcnt vmcnt(34)
	ds_write2_b32 v98, v28, v29 offset0:56 offset1:122
	s_waitcnt vmcnt(32)
	ds_write2_b32 v98, v30, v31 offset0:188 offset1:254
	s_waitcnt lgkmcnt(0)
	ds_read2_b32 v[52:53], v56 offset1:33
	s_lshr_b32 s39, s26, 5
	s_sub_i32 s43, 0, s39
	s_abs_i32 s42, s2
	s_ashr_i32 s41, s2, 31
	s_waitcnt lgkmcnt(0)
	v_mul_f32_e32 v52, v32, v52
	v_mul_f32_e32 v53, v33, v53
	v_cvt_pk_bf16_f32 v100, v52, v53
	ds_read2_b32 v[52:53], v56 offset0:66 offset1:99
	s_waitcnt lgkmcnt(0)
	v_mul_f32_e32 v52, v34, v52
	v_mul_f32_e32 v53, v35, v53
	v_cvt_pk_bf16_f32 v101, v52, v53
	ds_read2_b32 v[52:53], v56 offset0:132 offset1:165
	s_waitcnt lgkmcnt(0)
	v_mul_f32_e32 v52, v36, v52
	v_mul_f32_e32 v53, v37, v53
	v_cvt_pk_bf16_f32 v102, v52, v53
	ds_read2_b32 v[52:53], v56 offset0:198 offset1:231
	s_waitcnt lgkmcnt(0)
	v_mul_f32_e32 v52, v38, v52
	v_mul_f32_e32 v53, v39, v53
	v_cvt_pk_bf16_f32 v103, v52, v53
	v_cvt_f32_u32_e32 v52, s39
	v_rcp_iflag_f32_e32 v52, v52
	s_nop 0
	v_mul_f32_e32 v52, 0x4f7ffffe, v52
	v_cvt_u32_f32_e32 v52, v52
	s_nop 0
	v_readfirstlane_b32 s40, v52
	s_mul_i32 s43, s43, s40
	s_mul_hi_u32 s43, s40, s43
	s_add_i32 s40, s40, s43
	s_mul_hi_u32 s40, s42, s40
	s_mul_i32 s43, s40, s39
	s_sub_i32 s42, s42, s43
	s_add_i32 s43, s40, 1
	s_sub_i32 s50, s42, s39
	s_cmp_ge_u32 s42, s39
	s_cselect_b32 s40, s43, s40
	s_cselect_b32 s42, s50, s42
	s_add_i32 s43, s40, 1
	s_cmp_ge_u32 s42, s39
	s_cselect_b32 s40, s43, s40
	s_xor_b32 s40, s40, s41
	s_sub_i32 s40, s40, s41
	s_mul_i32 s39, s40, s39
	s_sub_i32 s39, s2, s39
	s_lshl_b32 s39, s39, 5
	s_ashr_i32 s42, s39, 31
	v_or_b32_e32 v52, s39, v55
	s_lshl_b32 s40, s40, 6
	s_mul_i32 s50, s42, s23
	v_mad_u64_u32 v[52:53], s[42:43], v52, s23, 0
	s_ashr_i32 s41, s40, 31
	v_add_u32_e32 v53, s50, v53
	v_lshl_add_u64 v[52:53], v[52:53], 1, s[28:29]
	s_lshl_b64 s[40:41], s[40:41], 1
	v_lshl_add_u64 v[104:105], v[52:53], 0, s[40:41]
	v_lshlrev_b64 v[52:53], 1, v[50:51]
	v_lshl_add_u64 v[104:105], v[104:105], 0, v[52:53]
	global_store_dwordx4 v[104:105], v[100:103], off
	ds_read2_b32 v[100:101], v56 offset0:8 offset1:41
	s_and_b64 vcc, exec, s[0:1]
	s_mov_b64 s[0:1], -1
	s_waitcnt lgkmcnt(0)
	v_mul_f32_e32 v100, v32, v100
	v_mul_f32_e32 v101, v33, v101
	v_cvt_pk_bf16_f32 v100, v100, v101
	ds_read2_b32 v[102:103], v56 offset0:74 offset1:107
	s_waitcnt lgkmcnt(0)
	v_mul_f32_e32 v101, v34, v102
	v_mul_f32_e32 v102, v35, v103
	v_cvt_pk_bf16_f32 v101, v101, v102
	ds_read2_b32 v[102:103], v56 offset0:140 offset1:173
	s_waitcnt lgkmcnt(0)
	v_mul_f32_e32 v102, v36, v102
	v_mul_f32_e32 v103, v37, v103
	v_cvt_pk_bf16_f32 v102, v102, v103
	ds_read2_b32 v[104:105], v56 offset0:206 offset1:239
	s_waitcnt lgkmcnt(0)
	v_mul_f32_e32 v103, v38, v104
	v_mul_f32_e32 v104, v39, v105
	v_cvt_pk_bf16_f32 v103, v103, v104
	v_or_b32_e32 v104, s39, v57
	v_mad_u64_u32 v[104:105], s[42:43], v104, s23, 0
	v_add_u32_e32 v105, s50, v105
	v_lshl_add_u64 v[104:105], v[104:105], 1, s[28:29]
	v_lshl_add_u64 v[104:105], v[104:105], 0, s[40:41]
	v_lshl_add_u64 v[104:105], v[104:105], 0, v[52:53]
	global_store_dwordx4 v[104:105], v[100:103], off
	ds_read2_b32 v[100:101], v56 offset0:16 offset1:49
	s_waitcnt lgkmcnt(0)
	v_mul_f32_e32 v100, v32, v100
	v_mul_f32_e32 v101, v33, v101
	v_cvt_pk_bf16_f32 v100, v100, v101
	ds_read2_b32 v[102:103], v56 offset0:82 offset1:115
	s_waitcnt lgkmcnt(0)
	v_mul_f32_e32 v101, v34, v102
	v_mul_f32_e32 v102, v35, v103
	v_cvt_pk_bf16_f32 v101, v101, v102
	ds_read2_b32 v[102:103], v56 offset0:148 offset1:181
	s_waitcnt lgkmcnt(0)
	v_mul_f32_e32 v102, v36, v102
	v_mul_f32_e32 v103, v37, v103
	v_cvt_pk_bf16_f32 v102, v102, v103
	ds_read2_b32 v[104:105], v56 offset0:214 offset1:247
	s_waitcnt lgkmcnt(0)
	v_mul_f32_e32 v103, v38, v104
	v_mul_f32_e32 v104, v39, v105
	v_cvt_pk_bf16_f32 v103, v103, v104
	v_or_b32_e32 v104, s39, v58
	v_mad_u64_u32 v[104:105], s[42:43], v104, s23, 0
	v_add_u32_e32 v105, s50, v105
	v_lshl_add_u64 v[104:105], v[104:105], 1, s[28:29]
	v_lshl_add_u64 v[104:105], v[104:105], 0, s[40:41]
	v_lshl_add_u64 v[104:105], v[104:105], 0, v[52:53]
	global_store_dwordx4 v[104:105], v[100:103], off
	ds_read2_b32 v[100:101], v56 offset0:24 offset1:57
	s_waitcnt lgkmcnt(0)
	v_mul_f32_e32 v100, v32, v100
	v_mul_f32_e32 v101, v33, v101
	v_cvt_pk_bf16_f32 v100, v100, v101
	ds_read2_b32 v[102:103], v56 offset0:90 offset1:123
	s_waitcnt lgkmcnt(0)
	v_mul_f32_e32 v101, v34, v102
	v_mul_f32_e32 v102, v35, v103
	v_cvt_pk_bf16_f32 v101, v101, v102
	ds_read2_b32 v[102:103], v56 offset0:156 offset1:189
	s_waitcnt lgkmcnt(0)
	v_mul_f32_e32 v102, v36, v102
	v_mul_f32_e32 v103, v37, v103
	v_cvt_pk_bf16_f32 v102, v102, v103
	ds_read2_b32 v[104:105], v56 offset0:222 offset1:255
	s_waitcnt lgkmcnt(0)
	v_mul_f32_e32 v103, v38, v104
	v_mul_f32_e32 v104, v39, v105
	v_cvt_pk_bf16_f32 v103, v103, v104
	v_or_b32_e32 v104, s39, v59
	v_mad_u64_u32 v[104:105], s[42:43], v104, s23, 0
	v_add_u32_e32 v105, s50, v105
	v_lshl_add_u64 v[104:105], v[104:105], 1, s[28:29]
	v_lshl_add_u64 v[104:105], v[104:105], 0, s[40:41]
	v_lshl_add_u64 v[104:105], v[104:105], 0, v[52:53]
	global_store_dwordx4 v[104:105], v[100:103], off
	s_waitcnt lgkmcnt(0)
	s_cbranch_vccnz .LBB0_31
	s_add_i32 s39, s49, s33
	s_cmpk_lt_i32 s39, 0x1880
	s_cselect_b64 s[42:43], -1, 0
	s_cmpk_gt_i32 s39, 0x187f
	s_cselect_b64 s[0:1], -1, 0
	s_mov_b64 s[40:41], 0
	s_and_b64 vcc, exec, s[0:1]
	s_cbranch_vccnz .LBB0_45
	s_cmpk_lt_i32 s39, 0x1800
	s_movk_i32 s26, 0x1800
	s_cbranch_scc1 .LBB0_48
	s_cmpk_gt_u32 s39, 0x183f
	s_cselect_b64 s[24:25], -1, 0
	s_and_b64 s[28:29], s[24:25], exec
	s_cselect_b32 s2, s45, 0xffffe800
	s_add_i32 s2, s33, s2
	s_add_i32 s2, s2, s49
	s_lshr_b32 s26, s2, 3
	s_and_b64 s[24:25], s[24:25], exec
	s_cselect_b32 s2, s46, 0x90000
	s_cselect_b32 s23, s19, s15
	s_cselect_b32 s28, s18, s14
	s_lshl_b64 s[24:25], s[26:27], 16
	s_add_u32 s24, s28, s24
	s_addc_u32 s25, s23, s25
	s_add_u32 s2, s92, s2
	s_addc_u32 s23, s93, 0
	s_lshl_b64 s[28:29], s[26:27], 15
	s_add_u32 s28, s2, s28
	s_addc_u32 s29, s23, s29
	s_movk_i32 s23, 0x80
	s_mov_b32 s26, s23
	s_mov_b32 s2, s44

.LBB0_59:
	s_waitcnt vmcnt(15)
	v_mul_f32_e32 v70, v1, v1
	v_mul_f32_e32 v71, v3, v3
	v_fmac_f32_e32 v70, v0, v0
	v_fmac_f32_e32 v71, v2, v2
	v_add_f32_e32 v70, v70, v71
	s_waitcnt vmcnt(14)
	v_mul_f32_e32 v71, v5, v5
	v_mul_f32_e32 v74, v7, v7
	v_fmac_f32_e32 v71, v4, v4
	v_fmac_f32_e32 v74, v6, v6
	v_add_f32_e32 v71, v71, v74
	v_add_f32_e32 v70, v71, v70
	s_waitcnt vmcnt(13)
	v_mul_f32_e32 v71, v9, v9
	v_mul_f32_e32 v74, v11, v11
	v_fmac_f32_e32 v71, v8, v8
	v_fmac_f32_e32 v74, v10, v10
	v_add_f32_e32 v71, v71, v74
	v_add_f32_e32 v70, v71, v70
	s_waitcnt vmcnt(12)
	v_mul_f32_e32 v71, v13, v13
	v_mul_f32_e32 v74, v15, v15
	v_fmac_f32_e32 v71, v12, v12
	v_fmac_f32_e32 v74, v14, v14
	v_add_f32_e32 v71, v71, v74
	v_add_f32_e32 v70, v71, v70
	s_waitcnt vmcnt(11)
	v_mul_f32_e32 v71, v17, v17
	v_mul_f32_e32 v74, v19, v19
	v_fmac_f32_e32 v71, v16, v16
	v_fmac_f32_e32 v74, v18, v18
	v_add_f32_e32 v71, v71, v74
	v_add_f32_e32 v70, v71, v70
	s_waitcnt vmcnt(10)
	v_mul_f32_e32 v71, v21, v21
	v_mul_f32_e32 v74, v23, v23
	v_fmac_f32_e32 v71, v20, v20
	v_fmac_f32_e32 v74, v22, v22
	v_add_f32_e32 v71, v71, v74
	v_add_f32_e32 v70, v71, v70
	s_waitcnt vmcnt(9)
	v_mul_f32_e32 v71, v25, v25
	v_mul_f32_e32 v74, v27, v27
	v_fmac_f32_e32 v71, v24, v24
	v_fmac_f32_e32 v74, v26, v26
	v_add_f32_e32 v71, v71, v74
	v_add_f32_e32 v70, v71, v70
	s_waitcnt vmcnt(8)
	v_mul_f32_e32 v71, v29, v29
	v_mul_f32_e32 v74, v31, v31
	v_fmac_f32_e32 v71, v28, v28
	v_fmac_f32_e32 v74, v30, v30
	v_add_f32_e32 v71, v71, v74
	v_add_f32_e32 v70, v71, v70
	v_and_b32_e32 v71, 64, v73
	v_add_u32_e32 v71, 64, v71
	v_xor_b32_e32 v74, 1, v73
	v_cmp_lt_i32_e32 vcc, v74, v71
	s_nop 1
	v_cndmask_b32_e32 v74, v73, v74, vcc
	v_lshlrev_b32_e32 v74, 2, v74
	ds_bpermute_b32 v75, v74, v70
	s_waitcnt lgkmcnt(0)
	v_add_f32_e32 v70, v70, v75
	v_xor_b32_e32 v75, 2, v73
	v_cmp_lt_i32_e32 vcc, v75, v71
	s_nop 1
	v_cndmask_b32_e32 v75, v73, v75, vcc
	v_lshlrev_b32_e32 v75, 2, v75
	ds_bpermute_b32 v76, v75, v70
	s_waitcnt lgkmcnt(0)
	v_add_f32_e32 v70, v70, v76
	v_xor_b32_e32 v76, 4, v73
	v_cmp_lt_i32_e32 vcc, v76, v71
	s_nop 1
	v_cndmask_b32_e32 v76, v73, v76, vcc
	v_lshlrev_b32_e32 v76, 2, v76
	ds_bpermute_b32 v77, v76, v70
	s_waitcnt lgkmcnt(0)
	v_add_f32_e32 v70, v70, v77
	v_xor_b32_e32 v77, 8, v73
	v_cmp_lt_i32_e32 vcc, v77, v71
	s_nop 1
	v_cndmask_b32_e32 v77, v73, v77, vcc
	v_lshlrev_b32_e32 v77, 2, v77
	ds_bpermute_b32 v78, v77, v70
	s_waitcnt lgkmcnt(0)
	v_add_f32_e32 v70, v70, v78
	v_xor_b32_e32 v78, 16, v73
	v_cmp_lt_i32_e32 vcc, v78, v71
	s_nop 1
	v_cndmask_b32_e32 v78, v73, v78, vcc
	v_lshlrev_b32_e32 v78, 2, v78
	ds_bpermute_b32 v79, v78, v70
	s_waitcnt lgkmcnt(0)
	v_add_f32_e32 v80, v70, v79
	v_xor_b32_e32 v70, 32, v73
	v_cmp_lt_i32_e32 vcc, v70, v71
	s_nop 1
	v_cndmask_b32_e32 v70, v73, v70, vcc
	v_lshlrev_b32_e32 v79, 2, v70
	ds_bpermute_b32 v81, v79, v80
	s_and_saveexec_b64 s[4:5], s[0:1]
	s_xor_b64 s[4:5], exec, s[4:5]
	s_ashr_i32 s23, s22, 31
	s_or_saveexec_b64 s[18:19], s[4:5]
	v_mov_b64_e32 v[70:71], s[22:23]
	s_xor_b64 exec, exec, s[18:19]
	s_cbranch_execz .LBB0_63
	s_waitcnt lgkmcnt(0)
	v_add_f32_e32 v70, v80, v81
	v_fmamk_f32 v70, v70, 0x3a000000, v64
	v_mul_f32_e32 v71, 0x4f800000, v70
	v_cmp_gt_f32_e32 vcc, s2, v70
	s_ashr_i32 s23, s22, 31
	s_nop 0
	v_cndmask_b32_e32 v70, v70, v71, vcc
	v_sqrt_f32_e32 v71, v70
	s_nop 0
	v_add_u32_e32 v80, -1, v71
	v_fma_f32 v82, -v80, v71, v70
	v_add_u32_e32 v81, 1, v71
	v_cmp_ge_f32_e64 s[4:5], 0, v82
	s_nop 1
	v_cndmask_b32_e64 v80, v71, v80, s[4:5]
	v_fma_f32 v71, -v81, v71, v70
	v_cmp_lt_f32_e64 s[4:5], 0, v71
	s_nop 1
	v_cndmask_b32_e64 v71, v80, v81, s[4:5]
	v_mul_f32_e32 v80, 0x37800000, v71
	v_cndmask_b32_e32 v71, v71, v80, vcc
	v_cmp_class_f32_e32 vcc, v70, v72
	s_nop 1
	v_cndmask_b32_e32 v70, v71, v70, vcc
	v_div_scale_f32 v71, s[4:5], v70, v70, 1.0
	v_rcp_f32_e32 v80, v71
	s_lshl_b64 s[4:5], s[22:23], 2
	s_add_u32 s4, s92, s4
	s_addc_u32 s5, s93, s5
	v_fma_f32 v81, -v71, v80, 1.0
	v_fmac_f32_e32 v80, v81, v80
	v_div_scale_f32 v81, vcc, 1.0, v70, 1.0
	v_mul_f32_e32 v82, v81, v80
	v_fma_f32 v83, -v71, v82, v81
	v_fmac_f32_e32 v82, v83, v80
	v_fma_f32 v71, -v71, v82, v81
	v_div_fmas_f32 v71, v71, v80, v82
	v_div_fixup_f32 v70, v71, v70, 1.0
	global_store_dword v65, v70, s[4:5]
	v_mov_b64_e32 v[70:71], s[22:23]

.LBB0_66:
	s_waitcnt vmcnt(8)
	v_mul_f32_e32 v70, v45, v45
	v_mul_f32_e32 v71, v47, v47
	v_fmac_f32_e32 v70, v44, v44
	v_fmac_f32_e32 v71, v46, v46
	v_add_f32_e32 v70, v70, v71
	v_mul_f32_e32 v71, v41, v41
	v_mul_f32_e32 v80, v43, v43
	v_fmac_f32_e32 v71, v40, v40
	v_fmac_f32_e32 v80, v42, v42
	v_add_f32_e32 v71, v71, v80
	v_add_f32_e32 v70, v71, v70
	v_mul_f32_e32 v71, v37, v37
	v_mul_f32_e32 v80, v39, v39
	v_fmac_f32_e32 v71, v36, v36
	v_fmac_f32_e32 v80, v38, v38
	v_add_f32_e32 v71, v71, v80
	v_add_f32_e32 v70, v71, v70
	v_mul_f32_e32 v71, v33, v33
	v_mul_f32_e32 v80, v35, v35
	v_fmac_f32_e32 v71, v32, v32
	v_fmac_f32_e32 v80, v34, v34
	v_add_f32_e32 v71, v71, v80
	v_add_f32_e32 v70, v71, v70
	v_mul_f32_e32 v71, v61, v61
	v_mul_f32_e32 v80, v63, v63
	v_fmac_f32_e32 v71, v60, v60
	v_fmac_f32_e32 v80, v62, v62
	v_add_f32_e32 v71, v71, v80
	v_add_f32_e32 v70, v71, v70
	v_mul_f32_e32 v71, v57, v57
	v_mul_f32_e32 v80, v59, v59
	v_fmac_f32_e32 v71, v56, v56
	v_fmac_f32_e32 v80, v58, v58
	v_add_f32_e32 v71, v71, v80
	v_add_f32_e32 v70, v71, v70
	v_mul_f32_e32 v71, v53, v53
	v_mul_f32_e32 v80, v55, v55
	v_fmac_f32_e32 v71, v52, v52
	v_fmac_f32_e32 v80, v54, v54
	v_add_f32_e32 v71, v71, v80
	v_add_f32_e32 v70, v71, v70
	v_mul_f32_e32 v71, v49, v49
	v_mul_f32_e32 v80, v51, v51
	v_fmac_f32_e32 v71, v48, v48
	v_fmac_f32_e32 v80, v50, v50
	v_add_f32_e32 v71, v71, v80
	v_add_f32_e32 v70, v71, v70
	ds_bpermute_b32 v71, v74, v70
	s_waitcnt lgkmcnt(0)
	v_add_f32_e32 v70, v70, v71
	ds_bpermute_b32 v71, v75, v70
	s_waitcnt lgkmcnt(0)
	v_add_f32_e32 v70, v70, v71
	ds_bpermute_b32 v71, v76, v70
	s_waitcnt lgkmcnt(0)
	v_add_f32_e32 v70, v70, v71
	ds_bpermute_b32 v71, v77, v70
	s_waitcnt lgkmcnt(0)
	v_add_f32_e32 v70, v70, v71
	ds_bpermute_b32 v71, v78, v70
	s_waitcnt lgkmcnt(0)
	v_add_f32_e32 v74, v70, v71
	ds_bpermute_b32 v75, v79, v74
	s_and_saveexec_b64 s[4:5], s[0:1]
	s_xor_b64 s[4:5], exec, s[4:5]
	s_ashr_i32 s9, s8, 31
	s_or_saveexec_b64 s[14:15], s[4:5]
	v_mov_b64_e32 v[70:71], s[8:9]
	s_xor_b64 exec, exec, s[14:15]
	s_cbranch_execz .LBB0_54
	s_waitcnt lgkmcnt(0)
	v_add_f32_e32 v70, v74, v75
	v_fmamk_f32 v70, v70, 0x3a000000, v64
	v_mul_f32_e32 v71, 0x4f800000, v70
	v_cmp_gt_f32_e32 vcc, s2, v70
	s_ashr_i32 s9, s8, 31
	s_nop 0
	v_cndmask_b32_e32 v70, v70, v71, vcc
	v_sqrt_f32_e32 v71, v70
	s_nop 0
	v_add_u32_e32 v74, -1, v71
	v_fma_f32 v76, -v74, v71, v70
	v_add_u32_e32 v75, 1, v71
	v_cmp_ge_f32_e64 s[4:5], 0, v76
	s_nop 1
	v_cndmask_b32_e64 v74, v71, v74, s[4:5]
	v_fma_f32 v71, -v75, v71, v70
	v_cmp_lt_f32_e64 s[4:5], 0, v71
	s_nop 1
	v_cndmask_b32_e64 v71, v74, v75, s[4:5]
	v_mul_f32_e32 v74, 0x37800000, v71
	v_cndmask_b32_e32 v71, v71, v74, vcc
	v_cmp_class_f32_e32 vcc, v70, v72
	s_nop 1
	v_cndmask_b32_e32 v70, v71, v70, vcc
	v_div_scale_f32 v71, s[4:5], v70, v70, 1.0
	v_rcp_f32_e32 v74, v71
	s_lshl_b64 s[4:5], s[8:9], 2
	s_add_u32 s4, s92, s4
	s_addc_u32 s5, s93, s5
	v_fma_f32 v75, -v71, v74, 1.0
	v_fmac_f32_e32 v74, v75, v74
	v_div_scale_f32 v75, vcc, 1.0, v70, 1.0
	v_mul_f32_e32 v76, v75, v74
	v_fma_f32 v77, -v71, v76, v75
	v_fmac_f32_e32 v76, v77, v74
	v_fma_f32 v71, -v71, v76, v75
	v_div_fmas_f32 v71, v71, v74, v76
	v_div_fixup_f32 v70, v71, v70, 1.0
	global_store_dword v65, v70, s[4:5]
	v_mov_b64_e32 v[70:71], s[8:9]
	s_branch .LBB0_54
.Lmy_c0_nob:
	s_waitcnt vmcnt(0)
	s_branch .LBB0_41
